# sample-row projections of the proj/w_out/w_down GEMMs as direct 16-column x 64-row tasks (fragment loads from global, full-K MFMA accumulation, no split-K atomics); batched XCD-rank check loads
# speedup vs baseline: 1.1986x; 1.0093x over previous
.LBB0_111:
	s_or_b64 exec, exec, s[4:5]
	s_barrier
	s_and_saveexec_b64 s[4:5], s[96:97]
	s_cbranch_execz .LBB0_122
	s_load_dword s8, s[0:1], 0x1b8
	s_waitcnt lgkmcnt(0)
	s_and_b32 s6, s8, 7
	s_cmp_lg_u32 s6, 0
	s_mov_b64 s[6:7], 0
	s_cbranch_scc1 .LBB0_121
	s_load_dwordx16 s[12:27], s[0:1], 0x140
	v_mov_b32_e32 v0, 0
	s_lshr_b32 s8, s8, 3
	s_waitcnt lgkmcnt(0)
	global_load_dword v1, v0, s[14:15] offset:64 sc1
	global_load_dword v253, v0, s[14:15] offset:68 sc1
	global_load_dword v254, v0, s[14:15] offset:72 sc1
	global_load_dword v255, v0, s[14:15] offset:76 sc1
	s_waitcnt vmcnt(0)
	v_xor_b32_e32 v1, s8, v1
	v_xor_b32_e32 v253, s8, v253
	v_xor_b32_e32 v254, s8, v254
	v_xor_b32_e32 v255, s8, v255
	v_or_b32_e32 v1, v1, v253
	v_or3_b32 v1, v1, v254, v255
	global_load_dword v253, v0, s[14:15] offset:80 sc1
	global_load_dword v254, v0, s[14:15] offset:84 sc1
	global_load_dword v255, v0, s[14:15] offset:88 sc1
	global_load_dword v0, v0, s[14:15] offset:92 sc1
	s_waitcnt vmcnt(0)
	v_xor_b32_e32 v253, s8, v253
	v_xor_b32_e32 v254, s8, v254
	v_xor_b32_e32 v255, s8, v255
	v_xor_b32_e32 v0, s8, v0
	v_or_b32_e32 v1, v1, v253
	v_or3_b32 v1, v1, v254, v255
	v_or_b32_e32 v1, v1, v0
	v_cmp_eq_u32_e64 s[6:7], 0, v1

.LBB0_122:
	s_or_b64 exec, exec, s[4:5]
	v_mov_b32_e32 v0, 0x10814
	s_waitcnt lgkmcnt(0)
	s_barrier
	ds_read_b32 v0, v0
	s_movk_i32 s3, 0x140
	v_bfe_u32 v136, v162, 4, 2
	v_lshrrev_b32_e32 v96, 3, v162
	v_lshlrev_b32_e32 v97, 3, v162
	s_waitcnt lgkmcnt(0)
	v_cmp_gt_i32_e32 vcc, s3, v0
	v_readfirstlane_b32 s63, v0
	s_and_b64 vcc, exec, vcc
	v_and_b32_e32 v98, 15, v162
	v_lshrrev_b32_e32 v101, 4, v162
	v_lshrrev_b32_e32 v100, 1, v162
	v_lshlrev_b32_e32 v137, 7, v162
	v_bitop3_b32 v138, v136, v219, 4 bitop3:0x36
	v_and_b32_e32 v102, 64, v162
	v_lshrrev_b32_e32 v139, 2, v162
	s_cbranch_vccnz .LBB0_124
.Lp1_task_done:
	v_lshrrev_b32_e32 v112, 3, v162
	v_xor_b32_e32 v2, v112, v162
	s_movk_i32 s3, 0x1c0
	v_lshlrev_b32_e32 v2, 4, v2
	v_and_or_b32 v99, v100, s3, v98
	v_bitop3_b32 v3, v101, v219, 3 bitop3:0x6c
	v_lshlrev_b32_e32 v4, 7, v112
	s_movk_i32 s3, 0x70
	v_and_b32_e32 v0, 56, v97
	v_mov_b32_e32 v1, 0
	v_lshlrev_b32_e32 v6, 7, v99
	v_lshlrev_b32_e32 v7, 4, v3
	v_and_or_b32 v103, v2, s3, v4
	v_and_b32_e32 v8, 0x2780, v137
	v_lshlrev_b32_e32 v9, 4, v138
	v_and_b32_e32 v3, 64, v162
	v_and_b32_e32 v2, 12, v139
	s_cbranch_execz .LBB0_125
	s_branch .LBB0_126
.LBB0_124:
.LBB0_125:
	v_readlane_b32 s4, v251, 6
	v_readlane_b32 s5, v251, 7
	v_readlane_b32 s6, v251, 20
	v_readlane_b32 s7, v251, 21
	v_readlane_b32 s8, v251, 18
	v_readlane_b32 s9, v251, 19
	s_cmp_ge_u32 s63, 0xa0
	s_cselect_b32 s10, 1, 0
	s_mul_i32 s11, s10, 0xa0
	s_sub_u32 s11, s63, s11
	s_add_u32 s4, s4, 0x2000000
	s_addc_u32 s5, s5, 0
	s_lshl_b32 s12, s11, 4
	s_mul_i32 s13, s12, 0x800
	s_lshl_b32 s14, s12, 2
	s_lshl_b32 s15, s10, 6
	v_and_b32_e32 v93, 63, v162
	v_lshrrev_b32_e32 v94, 6, v162
	v_and_b32_e32 v95, 15, v93
	v_lshrrev_b32_e32 v93, 4, v93
	v_lshl_add_u32 v94, v94, 4, s15
	v_add_u32_e32 v19, v94, v95
	v_mul_u32_u24_e32 v19, 0x800, v19
	v_lshl_add_u32 v19, v93, 5, v19
	v_mul_u32_u24_e32 v88, 0x800, v95
	v_lshl_add_u32 v88, v93, 5, v88
	v_add_u32_e32 v88, s13, v88
	v_lshl_add_u32 v94, v93, 2, v94
	v_mul_u32_u24_e32 v89, 0x2800, v94
	v_lshl_add_u32 v89, v95, 2, v89
	v_add_u32_e32 v89, s14, v89
	v_add_u32_e32 v90, 0x2800, v89
	v_add_u32_e32 v91, 0x2800, v90
	v_add_u32_e32 v92, 0x2800, v91
	v_mov_b32_e32 v20, 0
	v_mov_b32_e32 v21, 0
	v_mov_b32_e32 v22, 0
	v_mov_b32_e32 v23, 0
	global_load_dwordx4 v[24:27], v19, s[4:5] offset:0
	global_load_dwordx4 v[32:35], v88, s[6:7] offset:0
	global_load_dwordx4 v[28:31], v19, s[4:5] offset:16
	global_load_dwordx4 v[36:39], v88, s[6:7] offset:16
	global_load_dwordx4 v[40:43], v19, s[4:5] offset:128
	global_load_dwordx4 v[48:51], v88, s[6:7] offset:128
	global_load_dwordx4 v[44:47], v19, s[4:5] offset:144
	global_load_dwordx4 v[52:55], v88, s[6:7] offset:144
	global_load_dwordx4 v[56:59], v19, s[4:5] offset:256
	global_load_dwordx4 v[64:67], v88, s[6:7] offset:256
	global_load_dwordx4 v[60:63], v19, s[4:5] offset:272
	global_load_dwordx4 v[68:71], v88, s[6:7] offset:272
	global_load_dwordx4 v[72:75], v19, s[4:5] offset:384
	global_load_dwordx4 v[80:83], v88, s[6:7] offset:384
	global_load_dwordx4 v[76:79], v19, s[4:5] offset:400
	global_load_dwordx4 v[84:87], v88, s[6:7] offset:400
	s_waitcnt vmcnt(14)
	v_mfma_f32_16x16x32_bf16 v[20:23], v[24:27], v[32:35], v[20:23]
	s_waitcnt vmcnt(12)
	v_mfma_f32_16x16x32_bf16 v[20:23], v[28:31], v[36:39], v[20:23]
	s_nop 1
	global_load_dwordx4 v[24:27], v19, s[4:5] offset:512
	global_load_dwordx4 v[32:35], v88, s[6:7] offset:512
	global_load_dwordx4 v[28:31], v19, s[4:5] offset:528
	global_load_dwordx4 v[36:39], v88, s[6:7] offset:528
	s_waitcnt vmcnt(14)
	v_mfma_f32_16x16x32_bf16 v[20:23], v[40:43], v[48:51], v[20:23]
	s_waitcnt vmcnt(12)
	v_mfma_f32_16x16x32_bf16 v[20:23], v[44:47], v[52:55], v[20:23]
	s_nop 1
	global_load_dwordx4 v[40:43], v19, s[4:5] offset:640
	global_load_dwordx4 v[48:51], v88, s[6:7] offset:640
	global_load_dwordx4 v[44:47], v19, s[4:5] offset:656
	global_load_dwordx4 v[52:55], v88, s[6:7] offset:656
	s_waitcnt vmcnt(14)
	v_mfma_f32_16x16x32_bf16 v[20:23], v[56:59], v[64:67], v[20:23]
	s_waitcnt vmcnt(12)
	v_mfma_f32_16x16x32_bf16 v[20:23], v[60:63], v[68:71], v[20:23]
	s_nop 1
	global_load_dwordx4 v[56:59], v19, s[4:5] offset:768
	global_load_dwordx4 v[64:67], v88, s[6:7] offset:768
	global_load_dwordx4 v[60:63], v19, s[4:5] offset:784
	global_load_dwordx4 v[68:71], v88, s[6:7] offset:784
	s_waitcnt vmcnt(14)
	v_mfma_f32_16x16x32_bf16 v[20:23], v[72:75], v[80:83], v[20:23]
	s_waitcnt vmcnt(12)
	v_mfma_f32_16x16x32_bf16 v[20:23], v[76:79], v[84:87], v[20:23]
	s_nop 1
	global_load_dwordx4 v[72:75], v19, s[4:5] offset:896
	global_load_dwordx4 v[80:83], v88, s[6:7] offset:896
	global_load_dwordx4 v[76:79], v19, s[4:5] offset:912
	global_load_dwordx4 v[84:87], v88, s[6:7] offset:912
	s_waitcnt vmcnt(14)
	v_mfma_f32_16x16x32_bf16 v[20:23], v[24:27], v[32:35], v[20:23]
	s_waitcnt vmcnt(12)
	v_mfma_f32_16x16x32_bf16 v[20:23], v[28:31], v[36:39], v[20:23]
	s_nop 1
	global_load_dwordx4 v[24:27], v19, s[4:5] offset:1024
	global_load_dwordx4 v[32:35], v88, s[6:7] offset:1024
	global_load_dwordx4 v[28:31], v19, s[4:5] offset:1040
	global_load_dwordx4 v[36:39], v88, s[6:7] offset:1040
	s_waitcnt vmcnt(14)
	v_mfma_f32_16x16x32_bf16 v[20:23], v[40:43], v[48:51], v[20:23]
	s_waitcnt vmcnt(12)
	v_mfma_f32_16x16x32_bf16 v[20:23], v[44:47], v[52:55], v[20:23]
	s_nop 1
	global_load_dwordx4 v[40:43], v19, s[4:5] offset:1152
	global_load_dwordx4 v[48:51], v88, s[6:7] offset:1152
	global_load_dwordx4 v[44:47], v19, s[4:5] offset:1168
	global_load_dwordx4 v[52:55], v88, s[6:7] offset:1168
	s_waitcnt vmcnt(14)
	v_mfma_f32_16x16x32_bf16 v[20:23], v[56:59], v[64:67], v[20:23]
	s_waitcnt vmcnt(12)
	v_mfma_f32_16x16x32_bf16 v[20:23], v[60:63], v[68:71], v[20:23]
	s_nop 1
	global_load_dwordx4 v[56:59], v19, s[4:5] offset:1280
	global_load_dwordx4 v[64:67], v88, s[6:7] offset:1280
	global_load_dwordx4 v[60:63], v19, s[4:5] offset:1296
	global_load_dwordx4 v[68:71], v88, s[6:7] offset:1296
	s_waitcnt vmcnt(14)
	v_mfma_f32_16x16x32_bf16 v[20:23], v[72:75], v[80:83], v[20:23]
	s_waitcnt vmcnt(12)
	v_mfma_f32_16x16x32_bf16 v[20:23], v[76:79], v[84:87], v[20:23]
	s_nop 1
	global_load_dwordx4 v[72:75], v19, s[4:5] offset:1408
	global_load_dwordx4 v[80:83], v88, s[6:7] offset:1408
	global_load_dwordx4 v[76:79], v19, s[4:5] offset:1424
	global_load_dwordx4 v[84:87], v88, s[6:7] offset:1424
	s_waitcnt vmcnt(14)
	v_mfma_f32_16x16x32_bf16 v[20:23], v[24:27], v[32:35], v[20:23]
	s_waitcnt vmcnt(12)
	v_mfma_f32_16x16x32_bf16 v[20:23], v[28:31], v[36:39], v[20:23]
	s_nop 1
	global_load_dwordx4 v[24:27], v19, s[4:5] offset:1536
	global_load_dwordx4 v[32:35], v88, s[6:7] offset:1536
	global_load_dwordx4 v[28:31], v19, s[4:5] offset:1552
	global_load_dwordx4 v[36:39], v88, s[6:7] offset:1552
	s_waitcnt vmcnt(14)
	v_mfma_f32_16x16x32_bf16 v[20:23], v[40:43], v[48:51], v[20:23]
	s_waitcnt vmcnt(12)
	v_mfma_f32_16x16x32_bf16 v[20:23], v[44:47], v[52:55], v[20:23]
	s_nop 1
	global_load_dwordx4 v[40:43], v19, s[4:5] offset:1664
	global_load_dwordx4 v[48:51], v88, s[6:7] offset:1664
	global_load_dwordx4 v[44:47], v19, s[4:5] offset:1680
	global_load_dwordx4 v[52:55], v88, s[6:7] offset:1680
	s_waitcnt vmcnt(14)
	v_mfma_f32_16x16x32_bf16 v[20:23], v[56:59], v[64:67], v[20:23]
	s_waitcnt vmcnt(12)
	v_mfma_f32_16x16x32_bf16 v[20:23], v[60:63], v[68:71], v[20:23]
	s_nop 1
	global_load_dwordx4 v[56:59], v19, s[4:5] offset:1792
	global_load_dwordx4 v[64:67], v88, s[6:7] offset:1792
	global_load_dwordx4 v[60:63], v19, s[4:5] offset:1808
	global_load_dwordx4 v[68:71], v88, s[6:7] offset:1808
	s_waitcnt vmcnt(14)
	v_mfma_f32_16x16x32_bf16 v[20:23], v[72:75], v[80:83], v[20:23]
	s_waitcnt vmcnt(12)
	v_mfma_f32_16x16x32_bf16 v[20:23], v[76:79], v[84:87], v[20:23]
	s_nop 1
	global_load_dwordx4 v[72:75], v19, s[4:5] offset:1920
	global_load_dwordx4 v[80:83], v88, s[6:7] offset:1920
	global_load_dwordx4 v[76:79], v19, s[4:5] offset:1936
	global_load_dwordx4 v[84:87], v88, s[6:7] offset:1936
	s_waitcnt vmcnt(14)
	v_mfma_f32_16x16x32_bf16 v[20:23], v[24:27], v[32:35], v[20:23]
	s_waitcnt vmcnt(12)
	v_mfma_f32_16x16x32_bf16 v[20:23], v[28:31], v[36:39], v[20:23]
	s_waitcnt vmcnt(10)
	v_mfma_f32_16x16x32_bf16 v[20:23], v[40:43], v[48:51], v[20:23]
	s_waitcnt vmcnt(8)
	v_mfma_f32_16x16x32_bf16 v[20:23], v[44:47], v[52:55], v[20:23]
	s_waitcnt vmcnt(6)
	v_mfma_f32_16x16x32_bf16 v[20:23], v[56:59], v[64:67], v[20:23]
	s_waitcnt vmcnt(4)
	v_mfma_f32_16x16x32_bf16 v[20:23], v[60:63], v[68:71], v[20:23]
	s_waitcnt vmcnt(2)
	v_mfma_f32_16x16x32_bf16 v[20:23], v[72:75], v[80:83], v[20:23]
	s_waitcnt vmcnt(0)
	v_mfma_f32_16x16x32_bf16 v[20:23], v[76:79], v[84:87], v[20:23]
	s_nop 7
	s_nop 7
	global_store_dword v89, v20, s[8:9]
	global_store_dword v90, v21, s[8:9]
	global_store_dword v91, v22, s[8:9]
	global_store_dword v92, v23, s[8:9]
	s_branch .Lp1_task_done

.LBB0_687:
	s_cmp_gt_i32 s63, 0x7f
	v_lshlrev_b32_e32 v110, 2, v102
	v_lshlrev_b32_e32 v16, 2, v108
	v_lshlrev_b32_e32 v104, 12, v167
	s_cbranch_scc1 .LBB0_689
	v_readlane_b32 s4, v251, 6
	v_readlane_b32 s5, v251, 7
	v_readlane_b32 s6, v251, 0
	v_readlane_b32 s7, v251, 1
	v_readlane_b32 s8, v251, 48
	v_readlane_b32 s9, v251, 49
	s_lshr_b32 s10, s63, 6
	s_and_b32 s11, s63, 63
	s_add_u32 s4, s4, 0x2000000
	s_addc_u32 s5, s5, 0
	s_add_u32 s8, s8, 0x4000000
	s_addc_u32 s9, s9, 0
	s_lshl_b32 s12, s11, 4
	s_mul_i32 s13, s12, 0x800
	s_lshl_b32 s14, s12, 2
	s_lshl_b32 s15, s10, 6
	v_and_b32_e32 v93, 63, v162
	v_lshrrev_b32_e32 v94, 6, v162
	v_and_b32_e32 v95, 15, v93
	v_lshrrev_b32_e32 v93, 4, v93
	v_lshl_add_u32 v94, v94, 4, s15
	v_add_u32_e32 v19, v94, v95
	v_mul_u32_u24_e32 v19, 0x800, v19
	v_lshl_add_u32 v19, v93, 5, v19
	v_mul_u32_u24_e32 v88, 0x800, v95
	v_lshl_add_u32 v88, v93, 5, v88
	v_add_u32_e32 v88, s13, v88
	v_lshl_add_u32 v94, v93, 2, v94
	v_mul_u32_u24_e32 v89, 0x1000, v94
	v_lshl_add_u32 v89, v95, 2, v89
	v_add_u32_e32 v89, s14, v89
	v_add_u32_e32 v90, 0x1000, v89
	v_add_u32_e32 v91, 0x1000, v90
	v_add_u32_e32 v92, 0x1000, v91
	global_load_dword v20, v89, s[8:9]
	global_load_dword v21, v90, s[8:9]
	global_load_dword v22, v91, s[8:9]
	global_load_dword v23, v92, s[8:9]
	global_load_dwordx4 v[24:27], v19, s[4:5] offset:0
	global_load_dwordx4 v[32:35], v88, s[6:7] offset:0
	global_load_dwordx4 v[28:31], v19, s[4:5] offset:16
	global_load_dwordx4 v[36:39], v88, s[6:7] offset:16
	global_load_dwordx4 v[40:43], v19, s[4:5] offset:128
	global_load_dwordx4 v[48:51], v88, s[6:7] offset:128
	global_load_dwordx4 v[44:47], v19, s[4:5] offset:144
	global_load_dwordx4 v[52:55], v88, s[6:7] offset:144
	global_load_dwordx4 v[56:59], v19, s[4:5] offset:256
	global_load_dwordx4 v[64:67], v88, s[6:7] offset:256
	global_load_dwordx4 v[60:63], v19, s[4:5] offset:272
	global_load_dwordx4 v[68:71], v88, s[6:7] offset:272
	global_load_dwordx4 v[72:75], v19, s[4:5] offset:384
	global_load_dwordx4 v[80:83], v88, s[6:7] offset:384
	global_load_dwordx4 v[76:79], v19, s[4:5] offset:400
	global_load_dwordx4 v[84:87], v88, s[6:7] offset:400
	s_waitcnt vmcnt(14)
	v_mfma_f32_16x16x32_bf16 v[20:23], v[24:27], v[32:35], v[20:23]
	s_waitcnt vmcnt(12)
	v_mfma_f32_16x16x32_bf16 v[20:23], v[28:31], v[36:39], v[20:23]
	s_nop 1
	global_load_dwordx4 v[24:27], v19, s[4:5] offset:512
	global_load_dwordx4 v[32:35], v88, s[6:7] offset:512
	global_load_dwordx4 v[28:31], v19, s[4:5] offset:528
	global_load_dwordx4 v[36:39], v88, s[6:7] offset:528
	s_waitcnt vmcnt(14)
	v_mfma_f32_16x16x32_bf16 v[20:23], v[40:43], v[48:51], v[20:23]
	s_waitcnt vmcnt(12)
	v_mfma_f32_16x16x32_bf16 v[20:23], v[44:47], v[52:55], v[20:23]
	s_nop 1
	global_load_dwordx4 v[40:43], v19, s[4:5] offset:640
	global_load_dwordx4 v[48:51], v88, s[6:7] offset:640
	global_load_dwordx4 v[44:47], v19, s[4:5] offset:656
	global_load_dwordx4 v[52:55], v88, s[6:7] offset:656
	s_waitcnt vmcnt(14)
	v_mfma_f32_16x16x32_bf16 v[20:23], v[56:59], v[64:67], v[20:23]
	s_waitcnt vmcnt(12)
	v_mfma_f32_16x16x32_bf16 v[20:23], v[60:63], v[68:71], v[20:23]
	s_nop 1
	global_load_dwordx4 v[56:59], v19, s[4:5] offset:768
	global_load_dwordx4 v[64:67], v88, s[6:7] offset:768
	global_load_dwordx4 v[60:63], v19, s[4:5] offset:784
	global_load_dwordx4 v[68:71], v88, s[6:7] offset:784
	s_waitcnt vmcnt(14)
	v_mfma_f32_16x16x32_bf16 v[20:23], v[72:75], v[80:83], v[20:23]
	s_waitcnt vmcnt(12)
	v_mfma_f32_16x16x32_bf16 v[20:23], v[76:79], v[84:87], v[20:23]
	s_nop 1
	global_load_dwordx4 v[72:75], v19, s[4:5] offset:896
	global_load_dwordx4 v[80:83], v88, s[6:7] offset:896
	global_load_dwordx4 v[76:79], v19, s[4:5] offset:912
	global_load_dwordx4 v[84:87], v88, s[6:7] offset:912
	s_waitcnt vmcnt(14)
	v_mfma_f32_16x16x32_bf16 v[20:23], v[24:27], v[32:35], v[20:23]
	s_waitcnt vmcnt(12)
	v_mfma_f32_16x16x32_bf16 v[20:23], v[28:31], v[36:39], v[20:23]
	s_nop 1
	global_load_dwordx4 v[24:27], v19, s[4:5] offset:1024
	global_load_dwordx4 v[32:35], v88, s[6:7] offset:1024
	global_load_dwordx4 v[28:31], v19, s[4:5] offset:1040
	global_load_dwordx4 v[36:39], v88, s[6:7] offset:1040
	s_waitcnt vmcnt(14)
	v_mfma_f32_16x16x32_bf16 v[20:23], v[40:43], v[48:51], v[20:23]
	s_waitcnt vmcnt(12)
	v_mfma_f32_16x16x32_bf16 v[20:23], v[44:47], v[52:55], v[20:23]
	s_nop 1
	global_load_dwordx4 v[40:43], v19, s[4:5] offset:1152
	global_load_dwordx4 v[48:51], v88, s[6:7] offset:1152
	global_load_dwordx4 v[44:47], v19, s[4:5] offset:1168
	global_load_dwordx4 v[52:55], v88, s[6:7] offset:1168
	s_waitcnt vmcnt(14)
	v_mfma_f32_16x16x32_bf16 v[20:23], v[56:59], v[64:67], v[20:23]
	s_waitcnt vmcnt(12)
	v_mfma_f32_16x16x32_bf16 v[20:23], v[60:63], v[68:71], v[20:23]
	s_nop 1
	global_load_dwordx4 v[56:59], v19, s[4:5] offset:1280
	global_load_dwordx4 v[64:67], v88, s[6:7] offset:1280
	global_load_dwordx4 v[60:63], v19, s[4:5] offset:1296
	global_load_dwordx4 v[68:71], v88, s[6:7] offset:1296
	s_waitcnt vmcnt(14)
	v_mfma_f32_16x16x32_bf16 v[20:23], v[72:75], v[80:83], v[20:23]
	s_waitcnt vmcnt(12)
	v_mfma_f32_16x16x32_bf16 v[20:23], v[76:79], v[84:87], v[20:23]
	s_nop 1
	global_load_dwordx4 v[72:75], v19, s[4:5] offset:1408
	global_load_dwordx4 v[80:83], v88, s[6:7] offset:1408
	global_load_dwordx4 v[76:79], v19, s[4:5] offset:1424
	global_load_dwordx4 v[84:87], v88, s[6:7] offset:1424
	s_waitcnt vmcnt(14)
	v_mfma_f32_16x16x32_bf16 v[20:23], v[24:27], v[32:35], v[20:23]
	s_waitcnt vmcnt(12)
	v_mfma_f32_16x16x32_bf16 v[20:23], v[28:31], v[36:39], v[20:23]
	s_nop 1
	global_load_dwordx4 v[24:27], v19, s[4:5] offset:1536
	global_load_dwordx4 v[32:35], v88, s[6:7] offset:1536
	global_load_dwordx4 v[28:31], v19, s[4:5] offset:1552
	global_load_dwordx4 v[36:39], v88, s[6:7] offset:1552
	s_waitcnt vmcnt(14)
	v_mfma_f32_16x16x32_bf16 v[20:23], v[40:43], v[48:51], v[20:23]
	s_waitcnt vmcnt(12)
	v_mfma_f32_16x16x32_bf16 v[20:23], v[44:47], v[52:55], v[20:23]
	s_nop 1
	global_load_dwordx4 v[40:43], v19, s[4:5] offset:1664
	global_load_dwordx4 v[48:51], v88, s[6:7] offset:1664
	global_load_dwordx4 v[44:47], v19, s[4:5] offset:1680
	global_load_dwordx4 v[52:55], v88, s[6:7] offset:1680
	s_waitcnt vmcnt(14)
	v_mfma_f32_16x16x32_bf16 v[20:23], v[56:59], v[64:67], v[20:23]
	s_waitcnt vmcnt(12)
	v_mfma_f32_16x16x32_bf16 v[20:23], v[60:63], v[68:71], v[20:23]
	s_nop 1
	global_load_dwordx4 v[56:59], v19, s[4:5] offset:1792
	global_load_dwordx4 v[64:67], v88, s[6:7] offset:1792
	global_load_dwordx4 v[60:63], v19, s[4:5] offset:1808
	global_load_dwordx4 v[68:71], v88, s[6:7] offset:1808
	s_waitcnt vmcnt(14)
	v_mfma_f32_16x16x32_bf16 v[20:23], v[72:75], v[80:83], v[20:23]
	s_waitcnt vmcnt(12)
	v_mfma_f32_16x16x32_bf16 v[20:23], v[76:79], v[84:87], v[20:23]
	s_nop 1
	global_load_dwordx4 v[72:75], v19, s[4:5] offset:1920
	global_load_dwordx4 v[80:83], v88, s[6:7] offset:1920
	global_load_dwordx4 v[76:79], v19, s[4:5] offset:1936
	global_load_dwordx4 v[84:87], v88, s[6:7] offset:1936
	s_waitcnt vmcnt(14)
	v_mfma_f32_16x16x32_bf16 v[20:23], v[24:27], v[32:35], v[20:23]
	s_waitcnt vmcnt(12)
	v_mfma_f32_16x16x32_bf16 v[20:23], v[28:31], v[36:39], v[20:23]
	s_waitcnt vmcnt(10)
	v_mfma_f32_16x16x32_bf16 v[20:23], v[40:43], v[48:51], v[20:23]
	s_waitcnt vmcnt(8)
	v_mfma_f32_16x16x32_bf16 v[20:23], v[44:47], v[52:55], v[20:23]
	s_waitcnt vmcnt(6)
	v_mfma_f32_16x16x32_bf16 v[20:23], v[56:59], v[64:67], v[20:23]
	s_waitcnt vmcnt(4)
	v_mfma_f32_16x16x32_bf16 v[20:23], v[60:63], v[68:71], v[20:23]
	s_waitcnt vmcnt(2)
	v_mfma_f32_16x16x32_bf16 v[20:23], v[72:75], v[80:83], v[20:23]
	s_waitcnt vmcnt(0)
	v_mfma_f32_16x16x32_bf16 v[20:23], v[76:79], v[84:87], v[20:23]
	s_nop 7
	s_nop 7
	global_store_dword v89, v20, s[8:9]
	global_store_dword v90, v21, s[8:9]
	global_store_dword v91, v22, s[8:9]
	global_store_dword v92, v23, s[8:9]

.LBB0_925:
	s_cmpk_gt_i32 s63, 0x7f
	s_cbranch_scc1 .LBB0_927
	s_mov_b64 s[4:5], s[80:81]
	v_readlane_b32 s6, v251, 4
	v_readlane_b32 s7, v251, 5
	v_readlane_b32 s8, v251, 48
	v_readlane_b32 s9, v251, 49
	s_lshr_b32 s10, s63, 6
	s_and_b32 s11, s63, 63
	s_add_u32 s4, s4, 0x5800000
	s_addc_u32 s5, s5, 0
	s_add_u32 s8, s8, 0x4000000
	s_addc_u32 s9, s9, 0
	s_lshl_b32 s12, s11, 4
	s_mul_i32 s13, s12, 0x1600
	s_lshl_b32 s14, s12, 2
	s_lshl_b32 s15, s10, 6
	v_mbcnt_lo_u32_b32 v93, -1, 0
	v_mbcnt_hi_u32_b32 v93, -1, v93
	v_lshrrev_b32_e32 v94, 3, v96
	v_and_b32_e32 v95, 15, v93
	v_lshrrev_b32_e32 v93, 4, v93
	v_lshl_add_u32 v94, v94, 4, s15
	v_add_u32_e32 v19, v94, v95
	v_mul_u32_u24_e32 v19, 0x1600, v19
	v_lshl_add_u32 v19, v93, 5, v19
	v_mul_u32_u24_e32 v88, 0x1600, v95
	v_lshl_add_u32 v88, v93, 5, v88
	v_add_u32_e32 v88, s13, v88
	v_lshl_add_u32 v94, v93, 2, v94
	v_mul_u32_u24_e32 v89, 0x1000, v94
	v_lshl_add_u32 v89, v95, 2, v89
	v_add_u32_e32 v89, s14, v89
	v_add_u32_e32 v90, 0x1000, v89
	v_add_u32_e32 v91, 0x1000, v90
	v_add_u32_e32 v92, 0x1000, v91
	global_load_dword v20, v89, s[8:9]
	global_load_dword v21, v90, s[8:9]
	global_load_dword v22, v91, s[8:9]
	global_load_dword v23, v92, s[8:9]
	global_load_dwordx4 v[24:27], v19, s[4:5] offset:0
	global_load_dwordx4 v[32:35], v88, s[6:7] offset:0
	global_load_dwordx4 v[28:31], v19, s[4:5] offset:16
	global_load_dwordx4 v[36:39], v88, s[6:7] offset:16
	global_load_dwordx4 v[40:43], v19, s[4:5] offset:128
	global_load_dwordx4 v[48:51], v88, s[6:7] offset:128
	global_load_dwordx4 v[44:47], v19, s[4:5] offset:144
	global_load_dwordx4 v[52:55], v88, s[6:7] offset:144
	global_load_dwordx4 v[56:59], v19, s[4:5] offset:256
	global_load_dwordx4 v[64:67], v88, s[6:7] offset:256
	global_load_dwordx4 v[60:63], v19, s[4:5] offset:272
	global_load_dwordx4 v[68:71], v88, s[6:7] offset:272
	global_load_dwordx4 v[72:75], v19, s[4:5] offset:384
	global_load_dwordx4 v[80:83], v88, s[6:7] offset:384
	global_load_dwordx4 v[76:79], v19, s[4:5] offset:400
	global_load_dwordx4 v[84:87], v88, s[6:7] offset:400
	s_waitcnt vmcnt(14)
	v_mfma_f32_16x16x32_bf16 v[20:23], v[24:27], v[32:35], v[20:23]
	s_waitcnt vmcnt(12)
	v_mfma_f32_16x16x32_bf16 v[20:23], v[28:31], v[36:39], v[20:23]
	s_nop 1
	global_load_dwordx4 v[24:27], v19, s[4:5] offset:512
	global_load_dwordx4 v[32:35], v88, s[6:7] offset:512
	global_load_dwordx4 v[28:31], v19, s[4:5] offset:528
	global_load_dwordx4 v[36:39], v88, s[6:7] offset:528
	s_waitcnt vmcnt(14)
	v_mfma_f32_16x16x32_bf16 v[20:23], v[40:43], v[48:51], v[20:23]
	s_waitcnt vmcnt(12)
	v_mfma_f32_16x16x32_bf16 v[20:23], v[44:47], v[52:55], v[20:23]
	s_nop 1
	global_load_dwordx4 v[40:43], v19, s[4:5] offset:640
	global_load_dwordx4 v[48:51], v88, s[6:7] offset:640
	global_load_dwordx4 v[44:47], v19, s[4:5] offset:656
	global_load_dwordx4 v[52:55], v88, s[6:7] offset:656
	s_waitcnt vmcnt(14)
	v_mfma_f32_16x16x32_bf16 v[20:23], v[56:59], v[64:67], v[20:23]
	s_waitcnt vmcnt(12)
	v_mfma_f32_16x16x32_bf16 v[20:23], v[60:63], v[68:71], v[20:23]
	s_nop 1
	global_load_dwordx4 v[56:59], v19, s[4:5] offset:768
	global_load_dwordx4 v[64:67], v88, s[6:7] offset:768
	global_load_dwordx4 v[60:63], v19, s[4:5] offset:784
	global_load_dwordx4 v[68:71], v88, s[6:7] offset:784
	s_waitcnt vmcnt(14)
	v_mfma_f32_16x16x32_bf16 v[20:23], v[72:75], v[80:83], v[20:23]
	s_waitcnt vmcnt(12)
	v_mfma_f32_16x16x32_bf16 v[20:23], v[76:79], v[84:87], v[20:23]
	s_nop 1
	global_load_dwordx4 v[72:75], v19, s[4:5] offset:896
	global_load_dwordx4 v[80:83], v88, s[6:7] offset:896
	global_load_dwordx4 v[76:79], v19, s[4:5] offset:912
	global_load_dwordx4 v[84:87], v88, s[6:7] offset:912
	s_waitcnt vmcnt(14)
	v_mfma_f32_16x16x32_bf16 v[20:23], v[24:27], v[32:35], v[20:23]
	s_waitcnt vmcnt(12)
	v_mfma_f32_16x16x32_bf16 v[20:23], v[28:31], v[36:39], v[20:23]
	s_nop 1
	global_load_dwordx4 v[24:27], v19, s[4:5] offset:1024
	global_load_dwordx4 v[32:35], v88, s[6:7] offset:1024
	global_load_dwordx4 v[28:31], v19, s[4:5] offset:1040
	global_load_dwordx4 v[36:39], v88, s[6:7] offset:1040
	s_waitcnt vmcnt(14)
	v_mfma_f32_16x16x32_bf16 v[20:23], v[40:43], v[48:51], v[20:23]
	s_waitcnt vmcnt(12)
	v_mfma_f32_16x16x32_bf16 v[20:23], v[44:47], v[52:55], v[20:23]
	s_nop 1
	global_load_dwordx4 v[40:43], v19, s[4:5] offset:1152
	global_load_dwordx4 v[48:51], v88, s[6:7] offset:1152
	global_load_dwordx4 v[44:47], v19, s[4:5] offset:1168
	global_load_dwordx4 v[52:55], v88, s[6:7] offset:1168
	s_waitcnt vmcnt(14)
	v_mfma_f32_16x16x32_bf16 v[20:23], v[56:59], v[64:67], v[20:23]
	s_waitcnt vmcnt(12)
	v_mfma_f32_16x16x32_bf16 v[20:23], v[60:63], v[68:71], v[20:23]
	s_nop 1
	global_load_dwordx4 v[56:59], v19, s[4:5] offset:1280
	global_load_dwordx4 v[64:67], v88, s[6:7] offset:1280
	global_load_dwordx4 v[60:63], v19, s[4:5] offset:1296
	global_load_dwordx4 v[68:71], v88, s[6:7] offset:1296
	s_waitcnt vmcnt(14)
	v_mfma_f32_16x16x32_bf16 v[20:23], v[72:75], v[80:83], v[20:23]
	s_waitcnt vmcnt(12)
	v_mfma_f32_16x16x32_bf16 v[20:23], v[76:79], v[84:87], v[20:23]
	s_nop 1
	global_load_dwordx4 v[72:75], v19, s[4:5] offset:1408
	global_load_dwordx4 v[80:83], v88, s[6:7] offset:1408
	global_load_dwordx4 v[76:79], v19, s[4:5] offset:1424
	global_load_dwordx4 v[84:87], v88, s[6:7] offset:1424
	s_waitcnt vmcnt(14)
	v_mfma_f32_16x16x32_bf16 v[20:23], v[24:27], v[32:35], v[20:23]
	s_waitcnt vmcnt(12)
	v_mfma_f32_16x16x32_bf16 v[20:23], v[28:31], v[36:39], v[20:23]
	s_nop 1
	global_load_dwordx4 v[24:27], v19, s[4:5] offset:1536
	global_load_dwordx4 v[32:35], v88, s[6:7] offset:1536
	global_load_dwordx4 v[28:31], v19, s[4:5] offset:1552
	global_load_dwordx4 v[36:39], v88, s[6:7] offset:1552
	s_waitcnt vmcnt(14)
	v_mfma_f32_16x16x32_bf16 v[20:23], v[40:43], v[48:51], v[20:23]
	s_waitcnt vmcnt(12)
	v_mfma_f32_16x16x32_bf16 v[20:23], v[44:47], v[52:55], v[20:23]
	s_nop 1
	global_load_dwordx4 v[40:43], v19, s[4:5] offset:1664
	global_load_dwordx4 v[48:51], v88, s[6:7] offset:1664
	global_load_dwordx4 v[44:47], v19, s[4:5] offset:1680
	global_load_dwordx4 v[52:55], v88, s[6:7] offset:1680
	s_waitcnt vmcnt(14)
	v_mfma_f32_16x16x32_bf16 v[20:23], v[56:59], v[64:67], v[20:23]
	s_waitcnt vmcnt(12)
	v_mfma_f32_16x16x32_bf16 v[20:23], v[60:63], v[68:71], v[20:23]
	s_nop 1
	global_load_dwordx4 v[56:59], v19, s[4:5] offset:1792
	global_load_dwordx4 v[64:67], v88, s[6:7] offset:1792
	global_load_dwordx4 v[60:63], v19, s[4:5] offset:1808
	global_load_dwordx4 v[68:71], v88, s[6:7] offset:1808
	s_waitcnt vmcnt(14)
	v_mfma_f32_16x16x32_bf16 v[20:23], v[72:75], v[80:83], v[20:23]
	s_waitcnt vmcnt(12)
	v_mfma_f32_16x16x32_bf16 v[20:23], v[76:79], v[84:87], v[20:23]
	s_nop 1
	global_load_dwordx4 v[72:75], v19, s[4:5] offset:1920
	global_load_dwordx4 v[80:83], v88, s[6:7] offset:1920
	global_load_dwordx4 v[76:79], v19, s[4:5] offset:1936
	global_load_dwordx4 v[84:87], v88, s[6:7] offset:1936
	s_waitcnt vmcnt(14)
	v_mfma_f32_16x16x32_bf16 v[20:23], v[24:27], v[32:35], v[20:23]
	s_waitcnt vmcnt(12)
	v_mfma_f32_16x16x32_bf16 v[20:23], v[28:31], v[36:39], v[20:23]
	s_nop 1
	global_load_dwordx4 v[24:27], v19, s[4:5] offset:2048
	global_load_dwordx4 v[32:35], v88, s[6:7] offset:2048
	global_load_dwordx4 v[28:31], v19, s[4:5] offset:2064
	global_load_dwordx4 v[36:39], v88, s[6:7] offset:2064
	s_waitcnt vmcnt(14)
	v_mfma_f32_16x16x32_bf16 v[20:23], v[40:43], v[48:51], v[20:23]
	s_waitcnt vmcnt(12)
	v_mfma_f32_16x16x32_bf16 v[20:23], v[44:47], v[52:55], v[20:23]
	s_nop 1
	global_load_dwordx4 v[40:43], v19, s[4:5] offset:2176
	global_load_dwordx4 v[48:51], v88, s[6:7] offset:2176
	global_load_dwordx4 v[44:47], v19, s[4:5] offset:2192
	global_load_dwordx4 v[52:55], v88, s[6:7] offset:2192
	s_waitcnt vmcnt(14)
	v_mfma_f32_16x16x32_bf16 v[20:23], v[56:59], v[64:67], v[20:23]
	s_waitcnt vmcnt(12)
	v_mfma_f32_16x16x32_bf16 v[20:23], v[60:63], v[68:71], v[20:23]
	s_nop 1
	global_load_dwordx4 v[56:59], v19, s[4:5] offset:2304
	global_load_dwordx4 v[64:67], v88, s[6:7] offset:2304
	global_load_dwordx4 v[60:63], v19, s[4:5] offset:2320
	global_load_dwordx4 v[68:71], v88, s[6:7] offset:2320
	s_waitcnt vmcnt(14)
	v_mfma_f32_16x16x32_bf16 v[20:23], v[72:75], v[80:83], v[20:23]
	s_waitcnt vmcnt(12)
	v_mfma_f32_16x16x32_bf16 v[20:23], v[76:79], v[84:87], v[20:23]
	s_nop 1
	global_load_dwordx4 v[72:75], v19, s[4:5] offset:2432
	global_load_dwordx4 v[80:83], v88, s[6:7] offset:2432
	global_load_dwordx4 v[76:79], v19, s[4:5] offset:2448
	global_load_dwordx4 v[84:87], v88, s[6:7] offset:2448
	s_waitcnt vmcnt(14)
	v_mfma_f32_16x16x32_bf16 v[20:23], v[24:27], v[32:35], v[20:23]
	s_waitcnt vmcnt(12)
	v_mfma_f32_16x16x32_bf16 v[20:23], v[28:31], v[36:39], v[20:23]
	s_nop 1
	global_load_dwordx4 v[24:27], v19, s[4:5] offset:2560
	global_load_dwordx4 v[32:35], v88, s[6:7] offset:2560
	global_load_dwordx4 v[28:31], v19, s[4:5] offset:2576
	global_load_dwordx4 v[36:39], v88, s[6:7] offset:2576
	s_waitcnt vmcnt(14)
	v_mfma_f32_16x16x32_bf16 v[20:23], v[40:43], v[48:51], v[20:23]
	s_waitcnt vmcnt(12)
	v_mfma_f32_16x16x32_bf16 v[20:23], v[44:47], v[52:55], v[20:23]
	s_nop 1
	global_load_dwordx4 v[40:43], v19, s[4:5] offset:2688
	global_load_dwordx4 v[48:51], v88, s[6:7] offset:2688
	global_load_dwordx4 v[44:47], v19, s[4:5] offset:2704
	global_load_dwordx4 v[52:55], v88, s[6:7] offset:2704
	s_waitcnt vmcnt(14)
	v_mfma_f32_16x16x32_bf16 v[20:23], v[56:59], v[64:67], v[20:23]
	s_waitcnt vmcnt(12)
	v_mfma_f32_16x16x32_bf16 v[20:23], v[60:63], v[68:71], v[20:23]
	s_nop 1
	global_load_dwordx4 v[56:59], v19, s[4:5] offset:2816
	global_load_dwordx4 v[64:67], v88, s[6:7] offset:2816
	global_load_dwordx4 v[60:63], v19, s[4:5] offset:2832
	global_load_dwordx4 v[68:71], v88, s[6:7] offset:2832
	s_waitcnt vmcnt(14)
	v_mfma_f32_16x16x32_bf16 v[20:23], v[72:75], v[80:83], v[20:23]
	s_waitcnt vmcnt(12)
	v_mfma_f32_16x16x32_bf16 v[20:23], v[76:79], v[84:87], v[20:23]
	s_nop 1
	global_load_dwordx4 v[72:75], v19, s[4:5] offset:2944
	global_load_dwordx4 v[80:83], v88, s[6:7] offset:2944
	global_load_dwordx4 v[76:79], v19, s[4:5] offset:2960
	global_load_dwordx4 v[84:87], v88, s[6:7] offset:2960
	s_waitcnt vmcnt(14)
	v_mfma_f32_16x16x32_bf16 v[20:23], v[24:27], v[32:35], v[20:23]
	s_waitcnt vmcnt(12)
	v_mfma_f32_16x16x32_bf16 v[20:23], v[28:31], v[36:39], v[20:23]
	s_nop 1
	global_load_dwordx4 v[24:27], v19, s[4:5] offset:3072
	global_load_dwordx4 v[32:35], v88, s[6:7] offset:3072
	global_load_dwordx4 v[28:31], v19, s[4:5] offset:3088
	global_load_dwordx4 v[36:39], v88, s[6:7] offset:3088
	s_waitcnt vmcnt(14)
	v_mfma_f32_16x16x32_bf16 v[20:23], v[40:43], v[48:51], v[20:23]
	s_waitcnt vmcnt(12)
	v_mfma_f32_16x16x32_bf16 v[20:23], v[44:47], v[52:55], v[20:23]
	s_nop 1
	global_load_dwordx4 v[40:43], v19, s[4:5] offset:3200
	global_load_dwordx4 v[48:51], v88, s[6:7] offset:3200
	global_load_dwordx4 v[44:47], v19, s[4:5] offset:3216
	global_load_dwordx4 v[52:55], v88, s[6:7] offset:3216
	s_waitcnt vmcnt(14)
	v_mfma_f32_16x16x32_bf16 v[20:23], v[56:59], v[64:67], v[20:23]
	s_waitcnt vmcnt(12)
	v_mfma_f32_16x16x32_bf16 v[20:23], v[60:63], v[68:71], v[20:23]
	s_nop 1
	global_load_dwordx4 v[56:59], v19, s[4:5] offset:3328
	global_load_dwordx4 v[64:67], v88, s[6:7] offset:3328
	global_load_dwordx4 v[60:63], v19, s[4:5] offset:3344
	global_load_dwordx4 v[68:71], v88, s[6:7] offset:3344
	s_waitcnt vmcnt(14)
	v_mfma_f32_16x16x32_bf16 v[20:23], v[72:75], v[80:83], v[20:23]
	s_waitcnt vmcnt(12)
	v_mfma_f32_16x16x32_bf16 v[20:23], v[76:79], v[84:87], v[20:23]
	s_nop 1
	global_load_dwordx4 v[72:75], v19, s[4:5] offset:3456
	global_load_dwordx4 v[80:83], v88, s[6:7] offset:3456
	global_load_dwordx4 v[76:79], v19, s[4:5] offset:3472
	global_load_dwordx4 v[84:87], v88, s[6:7] offset:3472
	s_waitcnt vmcnt(14)
	v_mfma_f32_16x16x32_bf16 v[20:23], v[24:27], v[32:35], v[20:23]
	s_waitcnt vmcnt(12)
	v_mfma_f32_16x16x32_bf16 v[20:23], v[28:31], v[36:39], v[20:23]
	s_nop 1
	global_load_dwordx4 v[24:27], v19, s[4:5] offset:3584
	global_load_dwordx4 v[32:35], v88, s[6:7] offset:3584
	global_load_dwordx4 v[28:31], v19, s[4:5] offset:3600
	global_load_dwordx4 v[36:39], v88, s[6:7] offset:3600
	s_waitcnt vmcnt(14)
	v_mfma_f32_16x16x32_bf16 v[20:23], v[40:43], v[48:51], v[20:23]
	s_waitcnt vmcnt(12)
	v_mfma_f32_16x16x32_bf16 v[20:23], v[44:47], v[52:55], v[20:23]
	s_nop 1
	global_load_dwordx4 v[40:43], v19, s[4:5] offset:3712
	global_load_dwordx4 v[48:51], v88, s[6:7] offset:3712
	global_load_dwordx4 v[44:47], v19, s[4:5] offset:3728
	global_load_dwordx4 v[52:55], v88, s[6:7] offset:3728
	s_waitcnt vmcnt(14)
	v_mfma_f32_16x16x32_bf16 v[20:23], v[56:59], v[64:67], v[20:23]
	s_waitcnt vmcnt(12)
	v_mfma_f32_16x16x32_bf16 v[20:23], v[60:63], v[68:71], v[20:23]
	s_nop 1
	global_load_dwordx4 v[56:59], v19, s[4:5] offset:3840
	global_load_dwordx4 v[64:67], v88, s[6:7] offset:3840
	global_load_dwordx4 v[60:63], v19, s[4:5] offset:3856
	global_load_dwordx4 v[68:71], v88, s[6:7] offset:3856
	s_waitcnt vmcnt(14)
	v_mfma_f32_16x16x32_bf16 v[20:23], v[72:75], v[80:83], v[20:23]
	s_waitcnt vmcnt(12)
	v_mfma_f32_16x16x32_bf16 v[20:23], v[76:79], v[84:87], v[20:23]
	s_nop 1
	global_load_dwordx4 v[72:75], v19, s[4:5] offset:3968
	global_load_dwordx4 v[80:83], v88, s[6:7] offset:3968
	global_load_dwordx4 v[76:79], v19, s[4:5] offset:3984
	global_load_dwordx4 v[84:87], v88, s[6:7] offset:3984
	s_waitcnt vmcnt(14)
	v_mfma_f32_16x16x32_bf16 v[20:23], v[24:27], v[32:35], v[20:23]
	s_waitcnt vmcnt(12)
	v_mfma_f32_16x16x32_bf16 v[20:23], v[28:31], v[36:39], v[20:23]
	s_nop 1
	s_add_u32 s4, s4, 0x1000
	s_addc_u32 s5, s5, 0
	s_add_u32 s6, s6, 0x1000
	s_addc_u32 s7, s7, 0
	global_load_dwordx4 v[24:27], v19, s[4:5] offset:0
	global_load_dwordx4 v[32:35], v88, s[6:7] offset:0
	global_load_dwordx4 v[28:31], v19, s[4:5] offset:16
	global_load_dwordx4 v[36:39], v88, s[6:7] offset:16
	s_waitcnt vmcnt(14)
	v_mfma_f32_16x16x32_bf16 v[20:23], v[40:43], v[48:51], v[20:23]
	s_waitcnt vmcnt(12)
	v_mfma_f32_16x16x32_bf16 v[20:23], v[44:47], v[52:55], v[20:23]
	s_nop 1
	global_load_dwordx4 v[40:43], v19, s[4:5] offset:128
	global_load_dwordx4 v[48:51], v88, s[6:7] offset:128
	global_load_dwordx4 v[44:47], v19, s[4:5] offset:144
	global_load_dwordx4 v[52:55], v88, s[6:7] offset:144
	s_waitcnt vmcnt(14)
	v_mfma_f32_16x16x32_bf16 v[20:23], v[56:59], v[64:67], v[20:23]
	s_waitcnt vmcnt(12)
	v_mfma_f32_16x16x32_bf16 v[20:23], v[60:63], v[68:71], v[20:23]
	s_nop 1
	global_load_dwordx4 v[56:59], v19, s[4:5] offset:256
	global_load_dwordx4 v[64:67], v88, s[6:7] offset:256
	global_load_dwordx4 v[60:63], v19, s[4:5] offset:272
	global_load_dwordx4 v[68:71], v88, s[6:7] offset:272
	s_waitcnt vmcnt(14)
	v_mfma_f32_16x16x32_bf16 v[20:23], v[72:75], v[80:83], v[20:23]
	s_waitcnt vmcnt(12)
	v_mfma_f32_16x16x32_bf16 v[20:23], v[76:79], v[84:87], v[20:23]
	s_nop 1
	global_load_dwordx4 v[72:75], v19, s[4:5] offset:384
	global_load_dwordx4 v[80:83], v88, s[6:7] offset:384
	global_load_dwordx4 v[76:79], v19, s[4:5] offset:400
	global_load_dwordx4 v[84:87], v88, s[6:7] offset:400
	s_waitcnt vmcnt(14)
	v_mfma_f32_16x16x32_bf16 v[20:23], v[24:27], v[32:35], v[20:23]
	s_waitcnt vmcnt(12)
	v_mfma_f32_16x16x32_bf16 v[20:23], v[28:31], v[36:39], v[20:23]
	s_nop 1
	global_load_dwordx4 v[24:27], v19, s[4:5] offset:512
	global_load_dwordx4 v[32:35], v88, s[6:7] offset:512
	global_load_dwordx4 v[28:31], v19, s[4:5] offset:528
	global_load_dwordx4 v[36:39], v88, s[6:7] offset:528
	s_waitcnt vmcnt(14)
	v_mfma_f32_16x16x32_bf16 v[20:23], v[40:43], v[48:51], v[20:23]
	s_waitcnt vmcnt(12)
	v_mfma_f32_16x16x32_bf16 v[20:23], v[44:47], v[52:55], v[20:23]
	s_nop 1
	global_load_dwordx4 v[40:43], v19, s[4:5] offset:640
	global_load_dwordx4 v[48:51], v88, s[6:7] offset:640
	global_load_dwordx4 v[44:47], v19, s[4:5] offset:656
	global_load_dwordx4 v[52:55], v88, s[6:7] offset:656
	s_waitcnt vmcnt(14)
	v_mfma_f32_16x16x32_bf16 v[20:23], v[56:59], v[64:67], v[20:23]
	s_waitcnt vmcnt(12)
	v_mfma_f32_16x16x32_bf16 v[20:23], v[60:63], v[68:71], v[20:23]
	s_nop 1
	global_load_dwordx4 v[56:59], v19, s[4:5] offset:768
	global_load_dwordx4 v[64:67], v88, s[6:7] offset:768
	global_load_dwordx4 v[60:63], v19, s[4:5] offset:784
	global_load_dwordx4 v[68:71], v88, s[6:7] offset:784
	s_waitcnt vmcnt(14)
	v_mfma_f32_16x16x32_bf16 v[20:23], v[72:75], v[80:83], v[20:23]
	s_waitcnt vmcnt(12)
	v_mfma_f32_16x16x32_bf16 v[20:23], v[76:79], v[84:87], v[20:23]
	s_nop 1
	global_load_dwordx4 v[72:75], v19, s[4:5] offset:896
	global_load_dwordx4 v[80:83], v88, s[6:7] offset:896
	global_load_dwordx4 v[76:79], v19, s[4:5] offset:912
	global_load_dwordx4 v[84:87], v88, s[6:7] offset:912
	s_waitcnt vmcnt(14)
	v_mfma_f32_16x16x32_bf16 v[20:23], v[24:27], v[32:35], v[20:23]
	s_waitcnt vmcnt(12)
	v_mfma_f32_16x16x32_bf16 v[20:23], v[28:31], v[36:39], v[20:23]
	s_nop 1
	global_load_dwordx4 v[24:27], v19, s[4:5] offset:1024
	global_load_dwordx4 v[32:35], v88, s[6:7] offset:1024
	global_load_dwordx4 v[28:31], v19, s[4:5] offset:1040
	global_load_dwordx4 v[36:39], v88, s[6:7] offset:1040
	s_waitcnt vmcnt(14)
	v_mfma_f32_16x16x32_bf16 v[20:23], v[40:43], v[48:51], v[20:23]
	s_waitcnt vmcnt(12)
	v_mfma_f32_16x16x32_bf16 v[20:23], v[44:47], v[52:55], v[20:23]
	s_nop 1
	global_load_dwordx4 v[40:43], v19, s[4:5] offset:1152
	global_load_dwordx4 v[48:51], v88, s[6:7] offset:1152
	global_load_dwordx4 v[44:47], v19, s[4:5] offset:1168
	global_load_dwordx4 v[52:55], v88, s[6:7] offset:1168
	s_waitcnt vmcnt(14)
	v_mfma_f32_16x16x32_bf16 v[20:23], v[56:59], v[64:67], v[20:23]
	s_waitcnt vmcnt(12)
	v_mfma_f32_16x16x32_bf16 v[20:23], v[60:63], v[68:71], v[20:23]
	s_nop 1
	global_load_dwordx4 v[56:59], v19, s[4:5] offset:1280
	global_load_dwordx4 v[64:67], v88, s[6:7] offset:1280
	global_load_dwordx4 v[60:63], v19, s[4:5] offset:1296
	global_load_dwordx4 v[68:71], v88, s[6:7] offset:1296
	s_waitcnt vmcnt(14)
	v_mfma_f32_16x16x32_bf16 v[20:23], v[72:75], v[80:83], v[20:23]
	s_waitcnt vmcnt(12)
	v_mfma_f32_16x16x32_bf16 v[20:23], v[76:79], v[84:87], v[20:23]
	s_nop 1
	global_load_dwordx4 v[72:75], v19, s[4:5] offset:1408
	global_load_dwordx4 v[80:83], v88, s[6:7] offset:1408
	global_load_dwordx4 v[76:79], v19, s[4:5] offset:1424
	global_load_dwordx4 v[84:87], v88, s[6:7] offset:1424
	s_waitcnt vmcnt(14)
	v_mfma_f32_16x16x32_bf16 v[20:23], v[24:27], v[32:35], v[20:23]
	s_waitcnt vmcnt(12)
	v_mfma_f32_16x16x32_bf16 v[20:23], v[28:31], v[36:39], v[20:23]
	s_waitcnt vmcnt(10)
	v_mfma_f32_16x16x32_bf16 v[20:23], v[40:43], v[48:51], v[20:23]
	s_waitcnt vmcnt(8)
	v_mfma_f32_16x16x32_bf16 v[20:23], v[44:47], v[52:55], v[20:23]
	s_waitcnt vmcnt(6)
	v_mfma_f32_16x16x32_bf16 v[20:23], v[56:59], v[64:67], v[20:23]
	s_waitcnt vmcnt(4)
	v_mfma_f32_16x16x32_bf16 v[20:23], v[60:63], v[68:71], v[20:23]
	s_waitcnt vmcnt(2)
	v_mfma_f32_16x16x32_bf16 v[20:23], v[72:75], v[80:83], v[20:23]
	s_waitcnt vmcnt(0)
	v_mfma_f32_16x16x32_bf16 v[20:23], v[76:79], v[84:87], v[20:23]
	s_nop 7
	s_nop 7
	global_store_dword v89, v20, s[8:9]
	global_store_dword v90, v21, s[8:9]
	global_store_dword v91, v22, s[8:9]
	global_store_dword v92, v23, s[8:9]
